# DA loops: all K-fragment LDS reads hoisted to top of each half with counted lgkmcnt (on top of PV counted waits + GEMM K-loop reschedule)
# baseline (speedup 1.0000x reference)
; __device__ __forceinline__ void finishSM(f32x16& p0, f32x16& p1, float& l_reg, bf16x8& pa0, bf16x8& pa1, bf16x8& pa2, bf16x8& pa3) {
; #pragma unroll
;   for (int r = 0; r < 16; ++r) p1[r] = __builtin_amdgcn_exp2f(p1[r]);
;   float ps = 0;
; #pragma unroll
;   for (int r = 0; r < 16; ++r) ps += p0[r];
; #pragma unroll
;   for (int r = 0; r < 16; ++r) ps += p1[r];
;   { auto rr = __builtin_amdgcn_permlane32_swap(__float_as_uint(ps), __float_as_uint(ps), false, false);
;     ps = __uint_as_float(rr[0]) + __uint_as_float(rr[1]); }
;   l_reg += ps;
;     ...
;   PK4(p0, 0, pa0); PK4(p0, 8, pa1); PK4(p1, 0, pa2); PK4(p1, 8, pa3);
;     ...
; }
; template <int DQK, int QL>
; __device__ __forceinline__ void qkt(f32x16& p0, f32x16& p1, const char* Ks, const bf16x8 (&qr)[DQK / 16 - QL], const char* qlds, const int (&kofs)[4], float negM) {
;   constexpr int QR = DQK / 16 - QL;
; #pragma unroll
;   for (int r = 0; r < 16; ++r) { p0[r] = negM; p1[r] = negM; }
; #pragma unroll
;   for (int d0 = 0; d0 < DQK / 16; ++d0) {
;     const char* kp = Ks + kofs[d0 & 3] + (d0 >> 2) * 128;
;     bf16x8 b0 = *reinterpret_cast<const bf16x8*>(kp);
;     bf16x8 b1 = *reinterpret_cast<const bf16x8*>(kp + 32 * DQK * 2);
;     bf16x8 qf;
;     if constexpr (QL > 0) { if (d0 < QR) qf = qr[d0 < QR ? d0 : 0]; else qf = *reinterpret_cast<const bf16x8*>(qlds + (d0 - QR) * 1024); }
;     else qf = qr[d0];
;     p0 = __builtin_amdgcn_mfma_f32_32x32x16_bf16(b0, qf, p0, 0, 0, 0);
;     p1 = __builtin_amdgcn_mfma_f32_32x32x16_bf16(b1, qf, p1, 0, 0, 0);
;   }
; }
; template <int NCB> __device__ __forceinline__ int v_st(int k, int c) {
;   const int kk = (k & ~0xC) | ((k & 4) << 1) | ((k & 8) >> 1);
;   return ((kk >> 3) * NCB + (c >> 5)) * 512 + ((kk & 7) * 32 + (c & 31)) * 2;
; }
; __device__ __forceinline__ int v_rd_base(int lane) { return ((lane & 3) << 3) | (((lane >> 2) & 3) << 6) | (((lane >> 4) & 1) << 5) | (((lane >> 5) & 1) << 8); }
; template <int OFF> __device__ __forceinline__ s16x4 tr_read(int vb) {
;   s16x4 r; asm volatile("ds_read_b64_tr_b16 %0, %1 offset:%2" : "=&v"(r) : "v"(vb), "i"(OFF) : "memory"); return r;
; }
; template <int NCB, int D0> __device__ __forceinline__ void pv_one(f32x16& od, int vb, bf16x8 pa0, bf16x8 pa1, bf16x8 pa2, bf16x8 pa3) {
;   constexpr int KSTEP = NCB * 1024, HALF = NCB * 512, B0 = D0 * 512;
.LBB0_323:
	ds_read_b128 v[238:241], v174 offset:40960
	ds_read_b128 v[242:245], v175 offset:40960
	ds_read_b128 v[246:249], v173 offset:40960
	ds_read_b128 v[250:253], v176 offset:40960
	ds_read_b128 v[182:185], v174 offset:45056
	ds_read_b128 v[186:189], v175 offset:45056
	ds_read_b128 v[190:193], v173 offset:45056
	ds_read_b128 v[194:197], v176 offset:45056
	v_mov_b64_e32 v[126:127], s[18:19]
	v_mov_b64_e32 v[124:125], s[16:17]
	v_mov_b64_e32 v[122:123], s[14:15]
	v_mov_b64_e32 v[120:121], s[12:13]
	v_mov_b64_e32 v[118:119], s[10:11]
	v_mov_b64_e32 v[116:117], s[8:9]
	v_mov_b64_e32 v[114:115], s[6:7]
	v_mov_b64_e32 v[112:113], s[4:5]
	v_exp_f32_e32 v100, v68
	v_exp_f32_e32 v101, v69
	s_waitcnt lgkmcnt(7)
	v_mfma_f32_32x32x16_bf16 v[80:95], v[238:241], v[142:145], v[112:127]
	v_exp_f32_e32 v102, v70
	v_exp_f32_e32 v103, v71
	v_exp_f32_e32 v104, v72
	v_exp_f32_e32 v105, v73
	v_exp_f32_e32 v106, v74
	v_exp_f32_e32 v107, v75
	s_waitcnt lgkmcnt(6)
	v_mfma_f32_32x32x16_bf16 v[80:95], v[242:245], v[138:141], v[80:95]
	v_exp_f32_e32 v108, v76
	v_exp_f32_e32 v109, v77
	v_exp_f32_e32 v110, v78
	v_exp_f32_e32 v79, v79
	s_waitcnt lgkmcnt(5)
	v_mfma_f32_32x32x16_bf16 v[80:95], v[246:249], v[134:137], v[80:95]
	s_waitcnt lgkmcnt(4)
	v_mfma_f32_32x32x16_bf16 v[80:95], v[250:253], v[130:133], v[80:95]
	v_exp_f32_e32 v96, v64
	v_add_f32_e32 v64, 0, v165
	v_add_f32_e32 v64, v167, v64
	v_add_f32_e32 v64, v157, v64
	v_add_f32_e32 v64, v166, v64
	v_add_f32_e32 v64, v155, v64
	v_add_f32_e32 v64, v164, v64
	v_add_f32_e32 v64, v154, v64
	v_add_f32_e32 v64, v156, v64
	v_add_f32_e32 v64, v151, v64
	v_add_f32_e32 v64, v153, v64
	v_add_f32_e32 v64, v149, v64
	v_add_f32_e32 v64, v152, v64
	v_add_f32_e32 v64, v147, v64
	v_exp_f32_e32 v97, v65
	v_add_f32_e32 v64, v150, v64
	v_exp_f32_e32 v98, v66
	v_add_f32_e32 v64, v146, v64
	v_exp_f32_e32 v99, v67
	v_add_f32_e32 v64, v148, v64
	v_add_f32_e32 v64, v96, v64
	v_add_f32_e32 v64, v97, v64
	v_add_f32_e32 v64, v98, v64
	v_add_f32_e32 v64, v99, v64
	v_add_f32_e32 v64, v100, v64
	v_add_f32_e32 v64, v101, v64
	v_add_f32_e32 v64, v102, v64
	v_add_f32_e32 v64, v103, v64
	v_add_f32_e32 v64, v104, v64
	v_add_f32_e32 v64, v105, v64
	v_add_f32_e32 v64, v106, v64
	v_add_f32_e32 v64, v107, v64
	v_add_f32_e32 v64, v108, v64
	v_add_f32_e32 v64, v109, v64
	v_add_f32_e32 v64, v110, v64
	v_add_f32_e32 v180, v79, v64
	v_mov_b32_e32 v181, v180
	s_nop 1
	v_permlane32_swap_b32_e32 v180, v181
	v_cvt_pk_bf16_f32 v64, v165, v167
	v_cvt_pk_bf16_f32 v65, v157, v166
	v_cvt_pk_bf16_f32 v66, v155, v164
	v_cvt_pk_bf16_f32 v67, v154, v156
	v_cvt_pk_bf16_f32 v68, v151, v153
	v_cvt_pk_bf16_f32 v69, v149, v152
	v_cvt_pk_bf16_f32 v70, v147, v150
	v_cvt_pk_bf16_f32 v71, v146, v148
	v_cvt_pk_bf16_f32 v72, v96, v97
	v_cvt_pk_bf16_f32 v73, v98, v99
	v_cvt_pk_bf16_f32 v74, v100, v101
	v_cvt_pk_bf16_f32 v75, v102, v103
	v_cvt_pk_bf16_f32 v76, v104, v105
	v_cvt_pk_bf16_f32 v77, v106, v107
	v_cvt_pk_bf16_f32 v78, v108, v109
	v_cvt_pk_bf16_f32 v79, v110, v79
	s_nop 0
	v_permlane32_swap_b32_e32 v64, v66
	v_permlane32_swap_b32_e32 v65, v67
	v_permlane32_swap_b32_e32 v68, v70
	v_permlane32_swap_b32_e32 v69, v71
	v_permlane32_swap_b32_e32 v72, v74
	v_permlane32_swap_b32_e32 v73, v75
	v_permlane32_swap_b32_e32 v76, v78
	v_permlane32_swap_b32_e32 v77, v79
	v_lshl_add_u64 v[164:165], s[80:81], 0, v[158:159]
	s_waitcnt lgkmcnt(3)
	v_mfma_f32_32x32x16_bf16 v[96:111], v[182:185], v[142:145], v[112:127]
	v_lshl_add_u64 v[168:169], s[80:81], 0, v[160:161]
	v_lshl_add_u64 v[166:167], s[80:81], 0, v[162:163]
	s_nop 4
	v_add_co_u32_e32 v112, vcc, s90, v164
	s_waitcnt lgkmcnt(2)
	v_mfma_f32_32x32x16_bf16 v[96:111], v[186:189], v[138:141], v[96:111]
	s_nop 0
	v_addc_co_u32_e32 v113, vcc, 0, v165, vcc
	v_add_co_u32_e32 v114, vcc, s90, v168
	s_nop 1
	v_addc_co_u32_e32 v115, vcc, 0, v169, vcc
	global_load_dwordx4 v[146:149], v[112:113], off offset:1280
	global_load_dwordx4 v[150:153], v[114:115], off offset:2304
	v_add_co_u32_e32 v112, vcc, s90, v166
	s_waitcnt lgkmcnt(1)
	v_mfma_f32_32x32x16_bf16 v[96:111], v[190:193], v[134:137], v[96:111]
	s_nop 0
	v_addc_co_u32_e32 v113, vcc, 0, v167, vcc
	global_load_dwordx4 v[154:157], v[112:113], off offset:2304
	s_waitcnt lgkmcnt(0)
	v_mfma_f32_32x32x16_bf16 v[96:111], v[194:197], v[130:133], v[96:111]
	ds_read_b64_tr_b16 v[112:113], v172 offset:0
	ds_read_b64_tr_b16 v[114:115], v172 offset:0x800
	ds_read_b64_tr_b16 v[116:117], v172 offset:0x1000
	ds_read_b64_tr_b16 v[118:119], v172 offset:0x1800
	ds_read_b64_tr_b16 v[120:121], v172 offset:0x2000
	ds_read_b64_tr_b16 v[122:123], v172 offset:0x2800
	ds_read_b64_tr_b16 v[124:125], v172 offset:0x3000
	ds_read_b64_tr_b16 v[126:127], v172 offset:0x3800
	s_nop 0
	s_waitcnt lgkmcnt(6)
	v_mfma_f32_32x32x16_bf16 v[0:15], v[64:67], v[112:115], v[0:15]
	ds_read_b64_tr_b16 v[112:113], v172 offset:0x200
	ds_read_b64_tr_b16 v[114:115], v172 offset:0xa00
	s_waitcnt lgkmcnt(6)
	v_mfma_f32_32x32x16_bf16 v[0:15], v[68:71], v[116:119], v[0:15]
	ds_read_b64_tr_b16 v[116:117], v172 offset:0x1200
	ds_read_b64_tr_b16 v[118:119], v172 offset:0x1a00
	s_waitcnt lgkmcnt(6)
	v_mfma_f32_32x32x16_bf16 v[0:15], v[72:75], v[120:123], v[0:15]
	ds_read_b64_tr_b16 v[120:121], v172 offset:0x2200
	ds_read_b64_tr_b16 v[122:123], v172 offset:0x2a00
	s_waitcnt lgkmcnt(6)
	v_mfma_f32_32x32x16_bf16 v[0:15], v[76:79], v[124:127], v[0:15]
	ds_read_b64_tr_b16 v[124:125], v172 offset:0x3200
	ds_read_b64_tr_b16 v[126:127], v172 offset:0x3a00
	s_waitcnt lgkmcnt(6)
	v_mfma_f32_32x32x16_bf16 v[16:31], v[64:67], v[112:115], v[16:31]
	ds_read_b64_tr_b16 v[112:113], v172 offset:0x400
	ds_read_b64_tr_b16 v[114:115], v172 offset:0xc00
	s_waitcnt lgkmcnt(6)
; #define WAIT_L0() asm volatile("s_waitcnt lgkmcnt(0)" ::: "memory")
; #define SBAR() __builtin_amdgcn_sched_barrier(0)
; __device__ __forceinline__ int crow(int r, int hi) { return (r & 3) + 8 * (r >> 2) + 4 * hi; }
; template <bool GM>
; __device__ __forceinline__ void partialSM(f32x16& p0, f32x16& p1, bool mask, int kbase, int L, int qpos, int hi) {
;   if (mask) {
; #pragma unroll
;     for (int r = 0; r < 16; ++r) {
;       int k = kbase + crow(r, hi);
;       asm volatile("" : "+v"(k) : "v"(p0[r]));
;       bool ok = k < L;
;       if (GM) ok = ok && (k < 16 || abs(qpos - k) <= 128);
;       p0[r] = ok ? p0[r] : -1e30f;
;       int k2 = k + 32;
;       asm volatile("" : "+v"(k2) : "v"(p1[r]));
;       bool ok2 = k2 < L;
;       if (GM) ok2 = ok2 && (k2 < 16 || abs(qpos - k2) <= 128);
;       p1[r] = ok2 ? p1[r] : -1e30f;
;     }
; template <int NCB, int D0> __device__ __forceinline__ void pv_one(f32x16& od, int vb, bf16x8 pa0, bf16x8 pa1, bf16x8 pa2, bf16x8 pa3) {
;   constexpr int KSTEP = NCB * 1024, HALF = NCB * 512, B0 = D0 * 512;
;   const s16x4 l0 = tr_read<B0>(vb), h0 = tr_read<B0 + HALF>(vb), l1 = tr_read<B0 + KSTEP>(vb), h1 = tr_read<B0 + KSTEP + HALF>(vb);
;   const s16x4 l2 = tr_read<B0 + 2 * KSTEP>(vb), h2 = tr_read<B0 + 2 * KSTEP + HALF>(vb), l3 = tr_read<B0 + 3 * KSTEP>(vb), h3 = tr_read<B0 + 3 * KSTEP + HALF>(vb);
;   WAIT_L0(); SBAR();
;     ...
;   od = __builtin_amdgcn_mfma_f32_32x32x16_bf16(pa0, PK(l0, h0), od, 0, 0, 0);
;   od = __builtin_amdgcn_mfma_f32_32x32x16_bf16(pa1, PK(l1, h1), od, 0, 0, 0);
;   od = __builtin_amdgcn_mfma_f32_32x32x16_bf16(pa2, PK(l2, h2), od, 0, 0, 0);
;   od = __builtin_amdgcn_mfma_f32_32x32x16_bf16(pa3, PK(l3, h3), od, 0, 0, 0);
;     ...
; }
; template <int NCB> __device__ __forceinline__ void pv_all(f32x16 (&o)[NCB], int vb, bf16x8 pa0, bf16x8 pa1, bf16x8 pa2, bf16x8 pa3) {
;   pv_one<NCB, 0>(o[0], vb, pa0, pa1, pa2, pa3); pv_one<NCB, 1>(o[1], vb, pa0, pa1, pa2, pa3);
;   if constexpr (NCB == 4) { pv_one<NCB, 2>(o[2], vb, pa0, pa1, pa2, pa3); pv_one<NCB, 3>(o[3], vb, pa0, pa1, pa2, pa3); }
; }
	v_mfma_f32_32x32x16_bf16 v[16:31], v[68:71], v[116:119], v[16:31]
	ds_read_b64_tr_b16 v[116:117], v172 offset:0x1400
	ds_read_b64_tr_b16 v[118:119], v172 offset:0x1c00
	s_waitcnt lgkmcnt(6)
	v_mfma_f32_32x32x16_bf16 v[16:31], v[72:75], v[120:123], v[16:31]
	ds_read_b64_tr_b16 v[120:121], v172 offset:0x2400
	ds_read_b64_tr_b16 v[122:123], v172 offset:0x2c00
	s_waitcnt lgkmcnt(6)
	v_mfma_f32_32x32x16_bf16 v[16:31], v[76:79], v[124:127], v[16:31]
	ds_read_b64_tr_b16 v[124:125], v172 offset:0x3400
	ds_read_b64_tr_b16 v[126:127], v172 offset:0x3c00
	s_waitcnt lgkmcnt(6)
	v_mfma_f32_32x32x16_bf16 v[32:47], v[64:67], v[112:115], v[32:47]
	ds_read_b64_tr_b16 v[112:113], v172 offset:0x600
	ds_read_b64_tr_b16 v[114:115], v172 offset:0xe00
	s_waitcnt lgkmcnt(6)
	v_mfma_f32_32x32x16_bf16 v[32:47], v[68:71], v[116:119], v[32:47]
	ds_read_b64_tr_b16 v[116:117], v172 offset:0x1600
	ds_read_b64_tr_b16 v[118:119], v172 offset:0x1e00
	s_waitcnt lgkmcnt(6)
	v_mfma_f32_32x32x16_bf16 v[32:47], v[72:75], v[120:123], v[32:47]
	ds_read_b64_tr_b16 v[120:121], v172 offset:0x2600
	ds_read_b64_tr_b16 v[122:123], v172 offset:0x2e00
	s_waitcnt lgkmcnt(6)
	v_mfma_f32_32x32x16_bf16 v[32:47], v[76:79], v[124:127], v[32:47]
	ds_read_b64_tr_b16 v[124:125], v172 offset:0x3600
	ds_read_b64_tr_b16 v[126:127], v172 offset:0x3e00
	s_waitcnt lgkmcnt(6)
	v_mfma_f32_32x32x16_bf16 v[48:63], v[64:67], v[112:115], v[48:63]
	s_add_i32 s20, s36, 64
	s_cmp_le_i32 s20, s59
	v_add_u32_e32 v182, s36, v171
	s_waitcnt lgkmcnt(4)
	v_mfma_f32_32x32x16_bf16 v[48:63], v[68:71], v[116:119], v[48:63]
	s_waitcnt lgkmcnt(2)
	v_mfma_f32_32x32x16_bf16 v[48:63], v[72:75], v[120:123], v[48:63]
	s_waitcnt lgkmcnt(0)
	v_mfma_f32_32x32x16_bf16 v[48:63], v[76:79], v[124:127], v[48:63]
	s_cbranch_scc1 .LBB0_325
	v_add_u32_e32 v64, 64, v182
	s_nop 0
	v_cmp_gt_i32_e32 vcc, s94, v64
	v_add_u32_e32 v64, 32, v64
	s_nop 0
	v_cndmask_b32_e32 v80, v233, v80, vcc
	v_cmp_gt_i32_e32 vcc, s94, v64
	v_add_u32_e32 v64, 0x41, v182
	s_nop 0
	v_cndmask_b32_e32 v96, v233, v96, vcc
	v_cmp_gt_i32_e32 vcc, s94, v64
	v_add_u32_e32 v64, 32, v64
	s_nop 0
	v_cndmask_b32_e32 v81, v233, v81, vcc
	v_cmp_gt_i32_e32 vcc, s94, v64
	v_add_u32_e32 v64, 0x42, v182
	s_nop 0
	v_cndmask_b32_e32 v97, v233, v97, vcc
	v_cmp_gt_i32_e32 vcc, s94, v64
	v_add_u32_e32 v64, 32, v64
	s_nop 0
	v_cndmask_b32_e32 v82, v233, v82, vcc
	v_cmp_gt_i32_e32 vcc, s94, v64
	v_add_u32_e32 v64, 0x43, v182
	s_nop 0
	v_cndmask_b32_e32 v98, v233, v98, vcc
	v_cmp_gt_i32_e32 vcc, s94, v64
	v_add_u32_e32 v64, 32, v64
	s_nop 0
	v_cndmask_b32_e32 v83, v233, v83, vcc
	v_cmp_gt_i32_e32 vcc, s94, v64
	v_add_u32_e32 v64, 0x48, v182
	s_nop 0
	v_cndmask_b32_e32 v99, v233, v99, vcc
	v_cmp_gt_i32_e32 vcc, s94, v64
	v_add_u32_e32 v64, 32, v64
	s_nop 0
	v_cndmask_b32_e32 v84, v233, v84, vcc
	v_cmp_gt_i32_e32 vcc, s94, v64
	v_add_u32_e32 v64, 0x49, v182
	s_nop 0
	v_cndmask_b32_e32 v100, v233, v100, vcc
	v_cmp_gt_i32_e32 vcc, s94, v64
	v_add_u32_e32 v64, 32, v64
	s_nop 0
	v_cndmask_b32_e32 v85, v233, v85, vcc
	v_cmp_gt_i32_e32 vcc, s94, v64
	v_add_u32_e32 v64, 0x4a, v182
	s_nop 0
	v_cndmask_b32_e32 v101, v233, v101, vcc
	v_cmp_gt_i32_e32 vcc, s94, v64
	v_add_u32_e32 v64, 32, v64
	s_nop 0
	v_cndmask_b32_e32 v86, v233, v86, vcc
	v_cmp_gt_i32_e32 vcc, s94, v64
	v_add_u32_e32 v64, 0x4b, v182
	s_nop 0
	v_cndmask_b32_e32 v102, v233, v102, vcc
	v_cmp_gt_i32_e32 vcc, s94, v64
	v_add_u32_e32 v64, 32, v64
	s_nop 0
	v_cndmask_b32_e32 v87, v233, v87, vcc
	v_cmp_gt_i32_e32 vcc, s94, v64
	v_add_u32_e32 v64, 0x50, v182
	s_nop 0
	v_cndmask_b32_e32 v103, v233, v103, vcc
	v_cmp_gt_i32_e32 vcc, s94, v64
	v_add_u32_e32 v64, 32, v64
	s_nop 0
	v_cndmask_b32_e32 v88, v233, v88, vcc
	v_cmp_gt_i32_e32 vcc, s94, v64
	v_add_u32_e32 v64, 0x51, v182
	s_nop 0
	v_cndmask_b32_e32 v104, v233, v104, vcc
	v_cmp_gt_i32_e32 vcc, s94, v64
	v_add_u32_e32 v64, 32, v64
	s_nop 0
	v_cndmask_b32_e32 v89, v233, v89, vcc
	v_cmp_gt_i32_e32 vcc, s94, v64
	v_add_u32_e32 v64, 0x52, v182
	s_nop 0
	v_cndmask_b32_e32 v105, v233, v105, vcc
	v_cmp_gt_i32_e32 vcc, s94, v64
	v_add_u32_e32 v64, 32, v64
	s_nop 0
	v_cndmask_b32_e32 v90, v233, v90, vcc
	v_cmp_gt_i32_e32 vcc, s94, v64
	v_add_u32_e32 v64, 0x53, v182
	s_nop 0
	v_cndmask_b32_e32 v106, v233, v106, vcc
	v_cmp_gt_i32_e32 vcc, s94, v64
	v_add_u32_e32 v64, 32, v64
	s_nop 0
	v_cndmask_b32_e32 v91, v233, v91, vcc
	v_cmp_gt_i32_e32 vcc, s94, v64
	v_add_u32_e32 v64, 0x58, v182
	s_nop 0
	v_cndmask_b32_e32 v107, v233, v107, vcc
	v_cmp_gt_i32_e32 vcc, s94, v64
	v_add_u32_e32 v64, 32, v64
	s_nop 0
	v_cndmask_b32_e32 v92, v233, v92, vcc
	v_cmp_gt_i32_e32 vcc, s94, v64
	v_add_u32_e32 v64, 0x59, v182
	s_nop 0
	v_cndmask_b32_e32 v108, v233, v108, vcc
	v_cmp_gt_i32_e32 vcc, s94, v64
	v_add_u32_e32 v64, 32, v64
	s_nop 0
	v_cndmask_b32_e32 v93, v233, v93, vcc
	v_cmp_gt_i32_e32 vcc, s94, v64
	v_add_u32_e32 v64, 0x5a, v182
	s_nop 0
	v_cndmask_b32_e32 v109, v233, v109, vcc
	v_cmp_gt_i32_e32 vcc, s94, v64
	v_add_u32_e32 v64, 32, v64
	s_nop 0
	v_cndmask_b32_e32 v94, v233, v94, vcc
	v_cmp_gt_i32_e32 vcc, s94, v64
	v_add_u32_e32 v64, 0x5b, v182
	s_nop 0
	v_cndmask_b32_e32 v110, v233, v110, vcc
	v_cmp_gt_i32_e32 vcc, s94, v64
	v_add_u32_e32 v64, 32, v64
	s_nop 0
	v_cndmask_b32_e32 v95, v233, v95, vcc
	v_cmp_gt_i32_e32 vcc, s94, v64
	s_nop 1
	v_cndmask_b32_e32 v111, v233, v111, vcc
; #define WAIT_V0() asm volatile("s_waitcnt vmcnt(0)" ::: "memory")
; #define SBAR() __builtin_amdgcn_sched_barrier(0)
; #define SWRITE(b) do { FRESH_COORDS(); \
;     if constexpr (!KDMA) { _Pragma("unroll") for (int i = 0; i < KC; ++i) *reinterpret_cast<bf16x8*>(shm + (b) * SHM_K + klo[i]) = ks[i]; } \
;     _Pragma("unroll") for (int i = 0; i < VC; ++i) *reinterpret_cast<bf16x8*>(shm + (b) * SHM_V + vlo[i]) = vs[i]; } while (0)
; #define QKT(P0, P1, BUF) qkt<DQK, QL>(P0, P1, shm + K_OFF + (BUF) * SHM_K, qr, qlds, kofs, negM)
; template <int DQK, int QL>
; __device__ __forceinline__ void qkt(f32x16& p0, f32x16& p1, const char* Ks, const bf16x8 (&qr)[DQK / 16 - QL], const char* qlds, const int (&kofs)[4], float negM) {
;   constexpr int QR = DQK / 16 - QL;
; #pragma unroll
;   for (int r = 0; r < 16; ++r) { p0[r] = negM; p1[r] = negM; }
; #pragma unroll
;   for (int d0 = 0; d0 < DQK / 16; ++d0) {
;     const char* kp = Ks + kofs[d0 & 3] + (d0 >> 2) * 128;
;     bf16x8 b0 = *reinterpret_cast<const bf16x8*>(kp);
;     bf16x8 b1 = *reinterpret_cast<const bf16x8*>(kp + 32 * DQK * 2);
;     bf16x8 qf;
;     if constexpr (QL > 0) { if (d0 < QR) qf = qr[d0 < QR ? d0 : 0]; else qf = *reinterpret_cast<const bf16x8*>(qlds + (d0 - QR) * 1024); }
;     else qf = qr[d0];
;     p0 = __builtin_amdgcn_mfma_f32_32x32x16_bf16(b0, qf, p0, 0, 0, 0);
;     p1 = __builtin_amdgcn_mfma_f32_32x32x16_bf16(b1, qf, p1, 0, 0, 0);
;   }
; }
;     ...
;     partialSM<GM>(pB0, pB1, NEEDMASK(kb), kb, L, qpos, hi);
;     __syncthreads(); WAIT_V0(); SWRITE(0);
;     __syncthreads();
;     SBAR();
;     if constexpr (ONEP) { finishSM(pB0, pB1, l_reg, pa0, pa1, pa2, pa3); SBAR(); QKT(pA0, pA1, 0); }
;     else { QKT(pA0, pA1, 0); finishSM(pB0, pB1, l_reg, pa0, pa1, pa2, pa3); }
;     SBAR();
;     if (j + 2 < NT) SLOAD(TKEY(j + 2), 1);
.LBB0_325:
	s_barrier
	s_waitcnt vmcnt(0)
	s_waitcnt vmcnt(2)
	ds_write_b128 v179, v[146:149] offset:32768
	s_waitcnt vmcnt(1)
	ds_write_b128 v177, v[150:153]
	s_waitcnt vmcnt(0)
	ds_write_b128 v178, v[154:157]
	v_exp_f32_e32 v183, v80
	v_exp_f32_e32 v188, v81
	v_exp_f32_e32 v189, v82
	v_exp_f32_e32 v190, v83
	v_exp_f32_e32 v191, v84
	v_exp_f32_e32 v192, v85
	v_exp_f32_e32 v193, v86
	v_exp_f32_e32 v194, v87
	v_exp_f32_e32 v195, v88
	v_exp_f32_e32 v196, v89
	v_exp_f32_e32 v197, v90
	v_exp_f32_e32 v198, v91
	v_exp_f32_e32 v199, v92
	v_exp_f32_e32 v200, v93
	v_exp_f32_e32 v201, v94
	v_exp_f32_e32 v202, v95
	s_waitcnt lgkmcnt(0)
	s_barrier
	ds_read_b128 v[64:67], v174 offset:32768
	ds_read_b128 v[184:187], v174 offset:36864
	ds_read_b128 v[238:241], v175 offset:32768
	ds_read_b128 v[220:223], v175 offset:36864
	ds_read_b128 v[242:245], v173 offset:32768
	ds_read_b128 v[224:227], v173 offset:36864
	ds_read_b128 v[246:249], v176 offset:32768
	ds_read_b128 v[228:231], v176 offset:36864
	v_mov_b64_e32 v[126:127], s[18:19]
	v_mov_b64_e32 v[124:125], s[16:17]
	v_mov_b64_e32 v[122:123], s[14:15]
	v_mov_b64_e32 v[120:121], s[12:13]
	v_mov_b64_e32 v[118:119], s[10:11]
	v_mov_b64_e32 v[116:117], s[8:9]
	v_mov_b64_e32 v[114:115], s[6:7]
	v_mov_b64_e32 v[112:113], s[4:5]
	v_exp_f32_e32 v111, v111
	s_waitcnt lgkmcnt(7)
	v_mfma_f32_32x32x16_bf16 v[80:95], v[64:67], v[142:145], v[112:127]
	s_waitcnt lgkmcnt(6)
	v_mfma_f32_32x32x16_bf16 v[64:79], v[184:187], v[142:145], v[112:127]
	s_nop 6
	v_exp_f32_e32 v120, v102
	v_exp_f32_e32 v121, v103
	v_exp_f32_e32 v122, v104
	v_exp_f32_e32 v123, v105
	v_exp_f32_e32 v124, v106
	v_exp_f32_e32 v125, v107
	s_waitcnt lgkmcnt(5)
	v_mfma_f32_32x32x16_bf16 v[80:95], v[238:241], v[138:141], v[80:95]
	v_exp_f32_e32 v126, v108
	v_exp_f32_e32 v127, v109
	v_exp_f32_e32 v184, v110
	s_waitcnt lgkmcnt(4)
	v_mfma_f32_32x32x16_bf16 v[64:79], v[220:223], v[138:141], v[64:79]
	s_waitcnt lgkmcnt(3)
	v_mfma_f32_32x32x16_bf16 v[80:95], v[242:245], v[134:137], v[80:95]
	s_waitcnt lgkmcnt(2)
	v_mfma_f32_32x32x16_bf16 v[64:79], v[224:227], v[134:137], v[64:79]
	s_waitcnt lgkmcnt(1)
	v_mfma_f32_32x32x16_bf16 v[80:95], v[246:249], v[130:133], v[80:95]
	v_exp_f32_e32 v114, v96
	v_add_f32_e32 v96, 0, v183
	v_add_f32_e32 v96, v188, v96
	v_add_f32_e32 v96, v189, v96
	v_add_f32_e32 v96, v190, v96
	v_add_f32_e32 v96, v191, v96
	v_add_f32_e32 v96, v192, v96
	v_add_f32_e32 v96, v193, v96
	v_add_f32_e32 v96, v194, v96
	v_add_f32_e32 v96, v195, v96
	v_add_f32_e32 v96, v196, v96
	v_add_f32_e32 v96, v197, v96
	v_add_f32_e32 v96, v198, v96
	v_add_f32_e32 v96, v199, v96
	v_exp_f32_e32 v115, v97
	v_add_f32_e32 v96, v200, v96
	s_waitcnt lgkmcnt(0)
	v_mfma_f32_32x32x16_bf16 v[64:79], v[228:231], v[130:133], v[64:79]
	v_exp_f32_e32 v116, v98
	v_add_f32_e32 v96, v201, v96
	v_exp_f32_e32 v117, v99
	v_add_f32_e32 v96, v202, v96
	v_exp_f32_e32 v118, v100
	v_add_f32_e32 v96, v114, v96
	v_exp_f32_e32 v119, v101
	v_add_f32_e32 v96, v115, v96
	v_add_f32_e32 v96, v116, v96
	v_add_f32_e32 v96, v117, v96
	v_add_f32_e32 v96, v118, v96
	v_add_f32_e32 v96, v119, v96
	v_add_f32_e32 v96, v120, v96
	v_add_f32_e32 v96, v121, v96
	v_add_f32_e32 v96, v122, v96
	v_add_f32_e32 v96, v123, v96
	v_add_f32_e32 v96, v124, v96
	v_add_f32_e32 v96, v125, v96
	v_add_f32_e32 v96, v126, v96
	v_add_f32_e32 v96, v127, v96
	v_add_f32_e32 v96, v184, v96
	v_add_f32_e32 v112, v111, v96
	v_mov_b32_e32 v113, v112
	v_cvt_pk_bf16_f32 v96, v183, v188
	v_cvt_pk_bf16_f32 v97, v189, v190
	v_cvt_pk_bf16_f32 v98, v191, v192
	v_cvt_pk_bf16_f32 v99, v193, v194
	v_cvt_pk_bf16_f32 v100, v195, v196
	v_cvt_pk_bf16_f32 v101, v197, v198
	v_cvt_pk_bf16_f32 v102, v199, v200
	v_cvt_pk_bf16_f32 v103, v201, v202
	v_cvt_pk_bf16_f32 v104, v114, v115
	v_cvt_pk_bf16_f32 v105, v116, v117
	v_cvt_pk_bf16_f32 v106, v118, v119
	v_cvt_pk_bf16_f32 v107, v120, v121
	v_cvt_pk_bf16_f32 v108, v122, v123
	v_cvt_pk_bf16_f32 v109, v124, v125
	v_cvt_pk_bf16_f32 v110, v126, v127
	v_cvt_pk_bf16_f32 v111, v184, v111
	s_nop 1
	v_permlane32_swap_b32_e32 v112, v113
	v_permlane32_swap_b32_e32 v96, v98
	v_permlane32_swap_b32_e32 v97, v99
	v_permlane32_swap_b32_e32 v100, v102
	v_permlane32_swap_b32_e32 v101, v103
	v_permlane32_swap_b32_e32 v104, v106
	v_permlane32_swap_b32_e32 v105, v107
	v_permlane32_swap_b32_e32 v108, v110
	v_permlane32_swap_b32_e32 v109, v111
	s_cmp_lt_u32 s26, s58
	s_cselect_b64 s[22:23], -1, 0
	s_cmp_ge_u32 s26, s58
	s_cselect_b64 s[20:21], -1, 0
	s_and_b64 vcc, exec, s[20:21]
	s_cbranch_vccnz .LBB0_327
	v_add_co_u32_e32 v114, vcc, 0x593c000, v164
	s_nop 1
	v_addc_co_u32_e32 v115, vcc, 0, v165, vcc
	v_add_co_u32_e32 v116, vcc, 0x593c000, v168
	s_nop 1
	v_addc_co_u32_e32 v117, vcc, 0, v169, vcc
	global_load_dwordx4 v[146:149], v[114:115], off offset:1280
	global_load_dwordx4 v[150:153], v[116:117], off offset:2304
	v_add_co_u32_e32 v114, vcc, 0x593c000, v166
	s_nop 1
	v_addc_co_u32_e32 v115, vcc, 0, v167, vcc
	global_load_dwordx4 v[154:157], v[114:115], off offset:2304

; __device__ __forceinline__ void finishSM(f32x16& p0, f32x16& p1, float& l_reg, bf16x8& pa0, bf16x8& pa1, bf16x8& pa2, bf16x8& pa3) {
; #pragma unroll
;   for (int r = 0; r < 16; ++r) p1[r] = __builtin_amdgcn_exp2f(p1[r]);
;   float ps = 0;
; #pragma unroll
;   for (int r = 0; r < 16; ++r) ps += p0[r];
; #pragma unroll
;   for (int r = 0; r < 16; ++r) ps += p1[r];
;   { auto rr = __builtin_amdgcn_permlane32_swap(__float_as_uint(ps), __float_as_uint(ps), false, false);
;     ps = __uint_as_float(rr[0]) + __uint_as_float(rr[1]); }
;   l_reg += ps;
;     ...
;   PK4(p0, 0, pa0); PK4(p0, 8, pa1); PK4(p1, 0, pa2); PK4(p1, 8, pa3);
;     ...
; }
; template <int DQK, int QL>
; __device__ __forceinline__ void qkt(f32x16& p0, f32x16& p1, const char* Ks, const bf16x8 (&qr)[DQK / 16 - QL], const char* qlds, const int (&kofs)[4], float negM) {
;   constexpr int QR = DQK / 16 - QL;
; #pragma unroll
;   for (int r = 0; r < 16; ++r) { p0[r] = negM; p1[r] = negM; }
; #pragma unroll
;   for (int d0 = 0; d0 < DQK / 16; ++d0) {
;     const char* kp = Ks + kofs[d0 & 3] + (d0 >> 2) * 128;
;     bf16x8 b0 = *reinterpret_cast<const bf16x8*>(kp);
;     bf16x8 b1 = *reinterpret_cast<const bf16x8*>(kp + 32 * DQK * 2);
;     bf16x8 qf;
;     if constexpr (QL > 0) { if (d0 < QR) qf = qr[d0 < QR ? d0 : 0]; else qf = *reinterpret_cast<const bf16x8*>(qlds + (d0 - QR) * 1024); }
;     else qf = qr[d0];
;     p0 = __builtin_amdgcn_mfma_f32_32x32x16_bf16(b0, qf, p0, 0, 0, 0);
;     p1 = __builtin_amdgcn_mfma_f32_32x32x16_bf16(b1, qf, p1, 0, 0, 0);
;   }
; }
; template <int NCB> __device__ __forceinline__ int v_st(int k, int c) {
;   const int kk = (k & ~0xC) | ((k & 4) << 1) | ((k & 8) >> 1);
;   return ((kk >> 3) * NCB + (c >> 5)) * 512 + ((kk & 7) * 32 + (c & 31)) * 2;
; }
; __device__ __forceinline__ int v_rd_base(int lane) { return ((lane & 3) << 3) | (((lane >> 2) & 3) << 6) | (((lane >> 4) & 1) << 5) | (((lane >> 5) & 1) << 8); }
; template <int OFF> __device__ __forceinline__ s16x4 tr_read(int vb) {
;   s16x4 r; asm volatile("ds_read_b64_tr_b16 %0, %1 offset:%2" : "=&v"(r) : "v"(vb), "i"(OFF) : "memory"); return r;
; }
; template <int NCB, int D0> __device__ __forceinline__ void pv_one(f32x16& od, int vb, bf16x8 pa0, bf16x8 pa1, bf16x8 pa2, bf16x8 pa3) {
;   constexpr int KSTEP = NCB * 1024, HALF = NCB * 512, B0 = D0 * 512;
.LBB0_342:
	ds_read_b128 v[238:241], v174 offset:40960
	ds_read_b128 v[242:245], v175 offset:40960
	ds_read_b128 v[246:249], v173 offset:40960
	ds_read_b128 v[250:253], v176 offset:40960
	ds_read_b128 v[182:185], v174 offset:45056
	ds_read_b128 v[186:189], v175 offset:45056
	ds_read_b128 v[190:193], v173 offset:45056
	ds_read_b128 v[194:197], v176 offset:45056
	v_mov_b64_e32 v[126:127], s[18:19]
	v_mov_b64_e32 v[124:125], s[16:17]
	v_mov_b64_e32 v[122:123], s[14:15]
	v_mov_b64_e32 v[120:121], s[12:13]
	v_mov_b64_e32 v[118:119], s[10:11]
	v_mov_b64_e32 v[116:117], s[8:9]
	v_mov_b64_e32 v[114:115], s[6:7]
	v_mov_b64_e32 v[112:113], s[4:5]
	v_exp_f32_e32 v100, v68
	v_exp_f32_e32 v101, v69
	s_waitcnt lgkmcnt(7)
	v_mfma_f32_32x32x16_bf16 v[80:95], v[238:241], v[142:145], v[112:127]
	v_exp_f32_e32 v102, v70
	v_exp_f32_e32 v103, v71
	v_exp_f32_e32 v104, v72
	v_exp_f32_e32 v105, v73
	v_exp_f32_e32 v106, v74
	v_exp_f32_e32 v107, v75
	s_waitcnt lgkmcnt(6)
	v_mfma_f32_32x32x16_bf16 v[80:95], v[242:245], v[138:141], v[80:95]
	v_exp_f32_e32 v108, v76
	v_exp_f32_e32 v109, v77
	v_exp_f32_e32 v110, v78
	v_exp_f32_e32 v79, v79
	s_waitcnt lgkmcnt(5)
	v_mfma_f32_32x32x16_bf16 v[80:95], v[246:249], v[134:137], v[80:95]
	s_waitcnt lgkmcnt(4)
	v_mfma_f32_32x32x16_bf16 v[80:95], v[250:253], v[130:133], v[80:95]
	v_exp_f32_e32 v96, v64
	v_add_f32_e32 v64, 0, v165
	v_add_f32_e32 v64, v167, v64
	v_add_f32_e32 v64, v157, v64
	v_add_f32_e32 v64, v166, v64
	v_add_f32_e32 v64, v155, v64
	v_add_f32_e32 v64, v164, v64
	v_add_f32_e32 v64, v154, v64
	v_add_f32_e32 v64, v156, v64
	v_add_f32_e32 v64, v151, v64
	v_add_f32_e32 v64, v153, v64
	v_add_f32_e32 v64, v149, v64
	v_add_f32_e32 v64, v152, v64
	v_add_f32_e32 v64, v147, v64
	v_exp_f32_e32 v97, v65
	v_add_f32_e32 v64, v150, v64
	v_exp_f32_e32 v98, v66
	v_add_f32_e32 v64, v146, v64
	v_exp_f32_e32 v99, v67
	v_add_f32_e32 v64, v148, v64
	v_add_f32_e32 v64, v96, v64
	v_add_f32_e32 v64, v97, v64
	v_add_f32_e32 v64, v98, v64
	v_add_f32_e32 v64, v99, v64
	v_add_f32_e32 v64, v100, v64
	v_add_f32_e32 v64, v101, v64
	v_add_f32_e32 v64, v102, v64
	v_add_f32_e32 v64, v103, v64
	v_add_f32_e32 v64, v104, v64
	v_add_f32_e32 v64, v105, v64
	v_add_f32_e32 v64, v106, v64
	v_add_f32_e32 v64, v107, v64
	v_add_f32_e32 v64, v108, v64
	v_add_f32_e32 v64, v109, v64
	v_add_f32_e32 v64, v110, v64
	v_add_f32_e32 v180, v79, v64
	v_mov_b32_e32 v181, v180
	s_nop 1
	v_permlane32_swap_b32_e32 v180, v181
	v_cvt_pk_bf16_f32 v64, v165, v167
	v_cvt_pk_bf16_f32 v65, v157, v166
	v_cvt_pk_bf16_f32 v66, v155, v164
	v_cvt_pk_bf16_f32 v67, v154, v156
	v_cvt_pk_bf16_f32 v68, v151, v153
	v_cvt_pk_bf16_f32 v69, v149, v152
	v_cvt_pk_bf16_f32 v70, v147, v150
	v_cvt_pk_bf16_f32 v71, v146, v148
	v_cvt_pk_bf16_f32 v72, v96, v97
	v_cvt_pk_bf16_f32 v73, v98, v99
	v_cvt_pk_bf16_f32 v74, v100, v101
	v_cvt_pk_bf16_f32 v75, v102, v103
	v_cvt_pk_bf16_f32 v76, v104, v105
	v_cvt_pk_bf16_f32 v77, v106, v107
	v_cvt_pk_bf16_f32 v78, v108, v109
	v_cvt_pk_bf16_f32 v79, v110, v79
	s_nop 0
	v_permlane32_swap_b32_e32 v64, v66
	v_permlane32_swap_b32_e32 v65, v67
	v_permlane32_swap_b32_e32 v68, v70
	v_permlane32_swap_b32_e32 v69, v71
	v_permlane32_swap_b32_e32 v72, v74
	v_permlane32_swap_b32_e32 v73, v75
	v_permlane32_swap_b32_e32 v76, v78
	v_permlane32_swap_b32_e32 v77, v79
	v_lshl_add_u64 v[164:165], s[0:1], 0, v[158:159]
	s_waitcnt lgkmcnt(3)
	v_mfma_f32_32x32x16_bf16 v[96:111], v[182:185], v[142:145], v[112:127]
	v_lshl_add_u64 v[168:169], s[0:1], 0, v[160:161]
	v_lshl_add_u64 v[166:167], s[0:1], 0, v[162:163]
	s_nop 4
	v_add_co_u32_e32 v112, vcc, s90, v164
	s_waitcnt lgkmcnt(2)
	v_mfma_f32_32x32x16_bf16 v[96:111], v[186:189], v[138:141], v[96:111]
	s_nop 0
	v_addc_co_u32_e32 v113, vcc, 0, v165, vcc
	v_add_co_u32_e32 v114, vcc, s90, v168
	s_nop 1
	v_addc_co_u32_e32 v115, vcc, 0, v169, vcc
	global_load_dwordx4 v[146:149], v[112:113], off offset:1408
	global_load_dwordx4 v[150:153], v[114:115], off offset:2304
	v_add_co_u32_e32 v112, vcc, s90, v166
	s_waitcnt lgkmcnt(1)
	v_mfma_f32_32x32x16_bf16 v[96:111], v[190:193], v[134:137], v[96:111]
	s_nop 0
	v_addc_co_u32_e32 v113, vcc, 0, v167, vcc
	global_load_dwordx4 v[154:157], v[112:113], off offset:2304
	s_waitcnt lgkmcnt(0)
	v_mfma_f32_32x32x16_bf16 v[96:111], v[194:197], v[130:133], v[96:111]
	ds_read_b64_tr_b16 v[112:113], v172 offset:0
	ds_read_b64_tr_b16 v[114:115], v172 offset:0x800
	ds_read_b64_tr_b16 v[116:117], v172 offset:0x1000
	ds_read_b64_tr_b16 v[118:119], v172 offset:0x1800
	ds_read_b64_tr_b16 v[120:121], v172 offset:0x2000
	ds_read_b64_tr_b16 v[122:123], v172 offset:0x2800
	ds_read_b64_tr_b16 v[124:125], v172 offset:0x3000
	ds_read_b64_tr_b16 v[126:127], v172 offset:0x3800
	s_nop 0
	s_waitcnt lgkmcnt(6)
	v_mfma_f32_32x32x16_bf16 v[0:15], v[64:67], v[112:115], v[0:15]
	ds_read_b64_tr_b16 v[112:113], v172 offset:0x200
	ds_read_b64_tr_b16 v[114:115], v172 offset:0xa00
	s_waitcnt lgkmcnt(6)
	v_mfma_f32_32x32x16_bf16 v[0:15], v[68:71], v[116:119], v[0:15]
	ds_read_b64_tr_b16 v[116:117], v172 offset:0x1200
	ds_read_b64_tr_b16 v[118:119], v172 offset:0x1a00
	s_waitcnt lgkmcnt(6)
	v_mfma_f32_32x32x16_bf16 v[0:15], v[72:75], v[120:123], v[0:15]
	ds_read_b64_tr_b16 v[120:121], v172 offset:0x2200
	ds_read_b64_tr_b16 v[122:123], v172 offset:0x2a00
	s_waitcnt lgkmcnt(6)
	v_mfma_f32_32x32x16_bf16 v[0:15], v[76:79], v[124:127], v[0:15]
	ds_read_b64_tr_b16 v[124:125], v172 offset:0x3200
	ds_read_b64_tr_b16 v[126:127], v172 offset:0x3a00
	s_waitcnt lgkmcnt(6)
	v_mfma_f32_32x32x16_bf16 v[16:31], v[64:67], v[112:115], v[16:31]
	ds_read_b64_tr_b16 v[112:113], v172 offset:0x400
	ds_read_b64_tr_b16 v[114:115], v172 offset:0xc00
	s_waitcnt lgkmcnt(6)
; #define WAIT_L0() asm volatile("s_waitcnt lgkmcnt(0)" ::: "memory")
; #define SBAR() __builtin_amdgcn_sched_barrier(0)
; __device__ __forceinline__ int crow(int r, int hi) { return (r & 3) + 8 * (r >> 2) + 4 * hi; }
; template <bool GM>
; __device__ __forceinline__ void partialSM(f32x16& p0, f32x16& p1, bool mask, int kbase, int L, int qpos, int hi) {
;   if (mask) {
; #pragma unroll
;     for (int r = 0; r < 16; ++r) {
;       int k = kbase + crow(r, hi);
;       asm volatile("" : "+v"(k) : "v"(p0[r]));
;       bool ok = k < L;
;       if (GM) ok = ok && (k < 16 || abs(qpos - k) <= 128);
;       p0[r] = ok ? p0[r] : -1e30f;
;       int k2 = k + 32;
;       asm volatile("" : "+v"(k2) : "v"(p1[r]));
;       bool ok2 = k2 < L;
;       if (GM) ok2 = ok2 && (k2 < 16 || abs(qpos - k2) <= 128);
;       p1[r] = ok2 ? p1[r] : -1e30f;
;     }
; template <int NCB, int D0> __device__ __forceinline__ void pv_one(f32x16& od, int vb, bf16x8 pa0, bf16x8 pa1, bf16x8 pa2, bf16x8 pa3) {
;   constexpr int KSTEP = NCB * 1024, HALF = NCB * 512, B0 = D0 * 512;
;   const s16x4 l0 = tr_read<B0>(vb), h0 = tr_read<B0 + HALF>(vb), l1 = tr_read<B0 + KSTEP>(vb), h1 = tr_read<B0 + KSTEP + HALF>(vb);
;   const s16x4 l2 = tr_read<B0 + 2 * KSTEP>(vb), h2 = tr_read<B0 + 2 * KSTEP + HALF>(vb), l3 = tr_read<B0 + 3 * KSTEP>(vb), h3 = tr_read<B0 + 3 * KSTEP + HALF>(vb);
;   WAIT_L0(); SBAR();
;     ...
;   od = __builtin_amdgcn_mfma_f32_32x32x16_bf16(pa0, PK(l0, h0), od, 0, 0, 0);
;   od = __builtin_amdgcn_mfma_f32_32x32x16_bf16(pa1, PK(l1, h1), od, 0, 0, 0);
;   od = __builtin_amdgcn_mfma_f32_32x32x16_bf16(pa2, PK(l2, h2), od, 0, 0, 0);
;   od = __builtin_amdgcn_mfma_f32_32x32x16_bf16(pa3, PK(l3, h3), od, 0, 0, 0);
;     ...
; }
; template <int NCB> __device__ __forceinline__ void pv_all(f32x16 (&o)[NCB], int vb, bf16x8 pa0, bf16x8 pa1, bf16x8 pa2, bf16x8 pa3) {
;   pv_one<NCB, 0>(o[0], vb, pa0, pa1, pa2, pa3); pv_one<NCB, 1>(o[1], vb, pa0, pa1, pa2, pa3);
;   if constexpr (NCB == 4) { pv_one<NCB, 2>(o[2], vb, pa0, pa1, pa2, pa3); pv_one<NCB, 3>(o[3], vb, pa0, pa1, pa2, pa3); }
; }
	v_mfma_f32_32x32x16_bf16 v[16:31], v[68:71], v[116:119], v[16:31]
	ds_read_b64_tr_b16 v[116:117], v172 offset:0x1400
	ds_read_b64_tr_b16 v[118:119], v172 offset:0x1c00
	s_waitcnt lgkmcnt(6)
	v_mfma_f32_32x32x16_bf16 v[16:31], v[72:75], v[120:123], v[16:31]
	ds_read_b64_tr_b16 v[120:121], v172 offset:0x2400
	ds_read_b64_tr_b16 v[122:123], v172 offset:0x2c00
	s_waitcnt lgkmcnt(6)
	v_mfma_f32_32x32x16_bf16 v[16:31], v[76:79], v[124:127], v[16:31]
	ds_read_b64_tr_b16 v[124:125], v172 offset:0x3400
	ds_read_b64_tr_b16 v[126:127], v172 offset:0x3c00
	s_waitcnt lgkmcnt(6)
	v_mfma_f32_32x32x16_bf16 v[32:47], v[64:67], v[112:115], v[32:47]
	ds_read_b64_tr_b16 v[112:113], v172 offset:0x600
	ds_read_b64_tr_b16 v[114:115], v172 offset:0xe00
	s_waitcnt lgkmcnt(6)
	v_mfma_f32_32x32x16_bf16 v[32:47], v[68:71], v[116:119], v[32:47]
	ds_read_b64_tr_b16 v[116:117], v172 offset:0x1600
	ds_read_b64_tr_b16 v[118:119], v172 offset:0x1e00
	s_waitcnt lgkmcnt(6)
	v_mfma_f32_32x32x16_bf16 v[32:47], v[72:75], v[120:123], v[32:47]
	ds_read_b64_tr_b16 v[120:121], v172 offset:0x2600
	ds_read_b64_tr_b16 v[122:123], v172 offset:0x2e00
	s_waitcnt lgkmcnt(6)
	v_mfma_f32_32x32x16_bf16 v[32:47], v[76:79], v[124:127], v[32:47]
	ds_read_b64_tr_b16 v[124:125], v172 offset:0x3600
	ds_read_b64_tr_b16 v[126:127], v172 offset:0x3e00
	s_waitcnt lgkmcnt(6)
	v_mfma_f32_32x32x16_bf16 v[48:63], v[64:67], v[112:115], v[48:63]
	s_add_i32 s20, s36, 64
	s_cmp_le_i32 s20, s59
	v_add_u32_e32 v182, s36, v171
	s_waitcnt lgkmcnt(4)
	v_mfma_f32_32x32x16_bf16 v[48:63], v[68:71], v[116:119], v[48:63]
	s_waitcnt lgkmcnt(2)
	v_mfma_f32_32x32x16_bf16 v[48:63], v[72:75], v[120:123], v[48:63]
	s_waitcnt lgkmcnt(0)
	v_mfma_f32_32x32x16_bf16 v[48:63], v[76:79], v[124:127], v[48:63]
	s_cbranch_scc1 .LBB0_344
	v_add_u32_e32 v64, 64, v182
	s_nop 0
	v_cmp_gt_i32_e32 vcc, s94, v64
	v_add_u32_e32 v64, 32, v64
	s_nop 0
	v_cndmask_b32_e32 v80, v233, v80, vcc
	v_cmp_gt_i32_e32 vcc, s94, v64
	v_add_u32_e32 v64, 0x41, v182
	s_nop 0
	v_cndmask_b32_e32 v96, v233, v96, vcc
	v_cmp_gt_i32_e32 vcc, s94, v64
	v_add_u32_e32 v64, 32, v64
	s_nop 0
	v_cndmask_b32_e32 v81, v233, v81, vcc
	v_cmp_gt_i32_e32 vcc, s94, v64
	v_add_u32_e32 v64, 0x42, v182
	s_nop 0
	v_cndmask_b32_e32 v97, v233, v97, vcc
	v_cmp_gt_i32_e32 vcc, s94, v64
	v_add_u32_e32 v64, 32, v64
	s_nop 0
	v_cndmask_b32_e32 v82, v233, v82, vcc
	v_cmp_gt_i32_e32 vcc, s94, v64
	v_add_u32_e32 v64, 0x43, v182
	s_nop 0
	v_cndmask_b32_e32 v98, v233, v98, vcc
	v_cmp_gt_i32_e32 vcc, s94, v64
	v_add_u32_e32 v64, 32, v64
	s_nop 0
	v_cndmask_b32_e32 v83, v233, v83, vcc
	v_cmp_gt_i32_e32 vcc, s94, v64
	v_add_u32_e32 v64, 0x48, v182
	s_nop 0
	v_cndmask_b32_e32 v99, v233, v99, vcc
	v_cmp_gt_i32_e32 vcc, s94, v64
	v_add_u32_e32 v64, 32, v64
	s_nop 0
	v_cndmask_b32_e32 v84, v233, v84, vcc
	v_cmp_gt_i32_e32 vcc, s94, v64
	v_add_u32_e32 v64, 0x49, v182
	s_nop 0
	v_cndmask_b32_e32 v100, v233, v100, vcc
	v_cmp_gt_i32_e32 vcc, s94, v64
	v_add_u32_e32 v64, 32, v64
	s_nop 0
	v_cndmask_b32_e32 v85, v233, v85, vcc
	v_cmp_gt_i32_e32 vcc, s94, v64
	v_add_u32_e32 v64, 0x4a, v182
	s_nop 0
	v_cndmask_b32_e32 v101, v233, v101, vcc
	v_cmp_gt_i32_e32 vcc, s94, v64
	v_add_u32_e32 v64, 32, v64
	s_nop 0
	v_cndmask_b32_e32 v86, v233, v86, vcc
	v_cmp_gt_i32_e32 vcc, s94, v64
	v_add_u32_e32 v64, 0x4b, v182
	s_nop 0
	v_cndmask_b32_e32 v102, v233, v102, vcc
	v_cmp_gt_i32_e32 vcc, s94, v64
	v_add_u32_e32 v64, 32, v64
	s_nop 0
	v_cndmask_b32_e32 v87, v233, v87, vcc
	v_cmp_gt_i32_e32 vcc, s94, v64
	v_add_u32_e32 v64, 0x50, v182
	s_nop 0
	v_cndmask_b32_e32 v103, v233, v103, vcc
	v_cmp_gt_i32_e32 vcc, s94, v64
	v_add_u32_e32 v64, 32, v64
	s_nop 0
	v_cndmask_b32_e32 v88, v233, v88, vcc
	v_cmp_gt_i32_e32 vcc, s94, v64
	v_add_u32_e32 v64, 0x51, v182
	s_nop 0
	v_cndmask_b32_e32 v104, v233, v104, vcc
	v_cmp_gt_i32_e32 vcc, s94, v64
	v_add_u32_e32 v64, 32, v64
	s_nop 0
	v_cndmask_b32_e32 v89, v233, v89, vcc
	v_cmp_gt_i32_e32 vcc, s94, v64
	v_add_u32_e32 v64, 0x52, v182
	s_nop 0
	v_cndmask_b32_e32 v105, v233, v105, vcc
	v_cmp_gt_i32_e32 vcc, s94, v64
	v_add_u32_e32 v64, 32, v64
	s_nop 0
	v_cndmask_b32_e32 v90, v233, v90, vcc
	v_cmp_gt_i32_e32 vcc, s94, v64
	v_add_u32_e32 v64, 0x53, v182
	s_nop 0
	v_cndmask_b32_e32 v106, v233, v106, vcc
	v_cmp_gt_i32_e32 vcc, s94, v64
	v_add_u32_e32 v64, 32, v64
	s_nop 0
	v_cndmask_b32_e32 v91, v233, v91, vcc
	v_cmp_gt_i32_e32 vcc, s94, v64
	v_add_u32_e32 v64, 0x58, v182
	s_nop 0
	v_cndmask_b32_e32 v107, v233, v107, vcc
	v_cmp_gt_i32_e32 vcc, s94, v64
	v_add_u32_e32 v64, 32, v64
	s_nop 0
	v_cndmask_b32_e32 v92, v233, v92, vcc
	v_cmp_gt_i32_e32 vcc, s94, v64
	v_add_u32_e32 v64, 0x59, v182
	s_nop 0
	v_cndmask_b32_e32 v108, v233, v108, vcc
	v_cmp_gt_i32_e32 vcc, s94, v64
	v_add_u32_e32 v64, 32, v64
	s_nop 0
	v_cndmask_b32_e32 v93, v233, v93, vcc
	v_cmp_gt_i32_e32 vcc, s94, v64
	v_add_u32_e32 v64, 0x5a, v182
	s_nop 0
	v_cndmask_b32_e32 v109, v233, v109, vcc
	v_cmp_gt_i32_e32 vcc, s94, v64
	v_add_u32_e32 v64, 32, v64
	s_nop 0
	v_cndmask_b32_e32 v94, v233, v94, vcc
	v_cmp_gt_i32_e32 vcc, s94, v64
	v_add_u32_e32 v64, 0x5b, v182
	s_nop 0
	v_cndmask_b32_e32 v110, v233, v110, vcc
	v_cmp_gt_i32_e32 vcc, s94, v64
	v_add_u32_e32 v64, 32, v64
	s_nop 0
	v_cndmask_b32_e32 v95, v233, v95, vcc
	v_cmp_gt_i32_e32 vcc, s94, v64
	s_nop 1
	v_cndmask_b32_e32 v111, v233, v111, vcc
; #define WAIT_V0() asm volatile("s_waitcnt vmcnt(0)" ::: "memory")
; #define SBAR() __builtin_amdgcn_sched_barrier(0)
; #define SWRITE(b) do { FRESH_COORDS(); \
;     if constexpr (!KDMA) { _Pragma("unroll") for (int i = 0; i < KC; ++i) *reinterpret_cast<bf16x8*>(shm + (b) * SHM_K + klo[i]) = ks[i]; } \
;     _Pragma("unroll") for (int i = 0; i < VC; ++i) *reinterpret_cast<bf16x8*>(shm + (b) * SHM_V + vlo[i]) = vs[i]; } while (0)
; #define QKT(P0, P1, BUF) qkt<DQK, QL>(P0, P1, shm + K_OFF + (BUF) * SHM_K, qr, qlds, kofs, negM)
; template <int DQK, int QL>
; __device__ __forceinline__ void qkt(f32x16& p0, f32x16& p1, const char* Ks, const bf16x8 (&qr)[DQK / 16 - QL], const char* qlds, const int (&kofs)[4], float negM) {
;   constexpr int QR = DQK / 16 - QL;
; #pragma unroll
;   for (int r = 0; r < 16; ++r) { p0[r] = negM; p1[r] = negM; }
; #pragma unroll
;   for (int d0 = 0; d0 < DQK / 16; ++d0) {
;     const char* kp = Ks + kofs[d0 & 3] + (d0 >> 2) * 128;
;     bf16x8 b0 = *reinterpret_cast<const bf16x8*>(kp);
;     bf16x8 b1 = *reinterpret_cast<const bf16x8*>(kp + 32 * DQK * 2);
;     bf16x8 qf;
;     if constexpr (QL > 0) { if (d0 < QR) qf = qr[d0 < QR ? d0 : 0]; else qf = *reinterpret_cast<const bf16x8*>(qlds + (d0 - QR) * 1024); }
;     else qf = qr[d0];
;     p0 = __builtin_amdgcn_mfma_f32_32x32x16_bf16(b0, qf, p0, 0, 0, 0);
;     p1 = __builtin_amdgcn_mfma_f32_32x32x16_bf16(b1, qf, p1, 0, 0, 0);
;   }
; }
;     ...
;     partialSM<GM>(pB0, pB1, NEEDMASK(kb), kb, L, qpos, hi);
;     __syncthreads(); WAIT_V0(); SWRITE(0);
;     __syncthreads();
;     SBAR();
;     if constexpr (ONEP) { finishSM(pB0, pB1, l_reg, pa0, pa1, pa2, pa3); SBAR(); QKT(pA0, pA1, 0); }
;     else { QKT(pA0, pA1, 0); finishSM(pB0, pB1, l_reg, pa0, pa1, pa2, pa3); }
;     SBAR();
;     if (j + 2 < NT) SLOAD(TKEY(j + 2), 1);
.LBB0_344:
	s_barrier
	s_waitcnt vmcnt(0)
	s_waitcnt vmcnt(2)
	ds_write_b128 v179, v[146:149] offset:32768
	s_waitcnt vmcnt(1)
	ds_write_b128 v177, v[150:153]
	s_waitcnt vmcnt(0)
	ds_write_b128 v178, v[154:157]
	v_exp_f32_e32 v183, v80
	v_exp_f32_e32 v188, v81
	v_exp_f32_e32 v189, v82
	v_exp_f32_e32 v190, v83
	v_exp_f32_e32 v191, v84
	v_exp_f32_e32 v192, v85
	v_exp_f32_e32 v193, v86
	v_exp_f32_e32 v194, v87
	v_exp_f32_e32 v195, v88
	v_exp_f32_e32 v196, v89
	v_exp_f32_e32 v197, v90
	v_exp_f32_e32 v198, v91
	v_exp_f32_e32 v199, v92
	v_exp_f32_e32 v200, v93
	v_exp_f32_e32 v201, v94
	v_exp_f32_e32 v202, v95
	s_waitcnt lgkmcnt(0)
	s_barrier
	ds_read_b128 v[64:67], v174 offset:32768
	ds_read_b128 v[184:187], v174 offset:36864
	ds_read_b128 v[238:241], v175 offset:32768
	ds_read_b128 v[220:223], v175 offset:36864
	ds_read_b128 v[242:245], v173 offset:32768
	ds_read_b128 v[224:227], v173 offset:36864
	ds_read_b128 v[246:249], v176 offset:32768
	ds_read_b128 v[228:231], v176 offset:36864
	v_mov_b64_e32 v[126:127], s[18:19]
	v_mov_b64_e32 v[124:125], s[16:17]
	v_mov_b64_e32 v[122:123], s[14:15]
	v_mov_b64_e32 v[120:121], s[12:13]
	v_mov_b64_e32 v[118:119], s[10:11]
	v_mov_b64_e32 v[116:117], s[8:9]
	v_mov_b64_e32 v[114:115], s[6:7]
	v_mov_b64_e32 v[112:113], s[4:5]
	v_exp_f32_e32 v111, v111
	s_waitcnt lgkmcnt(7)
	v_mfma_f32_32x32x16_bf16 v[80:95], v[64:67], v[142:145], v[112:127]
	s_waitcnt lgkmcnt(6)
	v_mfma_f32_32x32x16_bf16 v[64:79], v[184:187], v[142:145], v[112:127]
	s_nop 6
	v_exp_f32_e32 v120, v102
	v_exp_f32_e32 v121, v103
	v_exp_f32_e32 v122, v104
	v_exp_f32_e32 v123, v105
	v_exp_f32_e32 v124, v106
	v_exp_f32_e32 v125, v107
	s_waitcnt lgkmcnt(5)
	v_mfma_f32_32x32x16_bf16 v[80:95], v[238:241], v[138:141], v[80:95]
	v_exp_f32_e32 v126, v108
	v_exp_f32_e32 v127, v109
	v_exp_f32_e32 v184, v110
	s_waitcnt lgkmcnt(4)
	v_mfma_f32_32x32x16_bf16 v[64:79], v[220:223], v[138:141], v[64:79]
	s_waitcnt lgkmcnt(3)
	v_mfma_f32_32x32x16_bf16 v[80:95], v[242:245], v[134:137], v[80:95]
	s_waitcnt lgkmcnt(2)
	v_mfma_f32_32x32x16_bf16 v[64:79], v[224:227], v[134:137], v[64:79]
	s_waitcnt lgkmcnt(1)
	v_mfma_f32_32x32x16_bf16 v[80:95], v[246:249], v[130:133], v[80:95]
	v_exp_f32_e32 v114, v96
	v_add_f32_e32 v96, 0, v183
	v_add_f32_e32 v96, v188, v96
	v_add_f32_e32 v96, v189, v96
	v_add_f32_e32 v96, v190, v96
	v_add_f32_e32 v96, v191, v96
	v_add_f32_e32 v96, v192, v96
	v_add_f32_e32 v96, v193, v96
	v_add_f32_e32 v96, v194, v96
	v_add_f32_e32 v96, v195, v96
	v_add_f32_e32 v96, v196, v96
	v_add_f32_e32 v96, v197, v96
	v_add_f32_e32 v96, v198, v96
	v_add_f32_e32 v96, v199, v96
	v_exp_f32_e32 v115, v97
	v_add_f32_e32 v96, v200, v96
	s_waitcnt lgkmcnt(0)
	v_mfma_f32_32x32x16_bf16 v[64:79], v[228:231], v[130:133], v[64:79]
	v_exp_f32_e32 v116, v98
	v_add_f32_e32 v96, v201, v96
	v_exp_f32_e32 v117, v99
	v_add_f32_e32 v96, v202, v96
	v_exp_f32_e32 v118, v100
	v_add_f32_e32 v96, v114, v96
	v_exp_f32_e32 v119, v101
	v_add_f32_e32 v96, v115, v96
	v_add_f32_e32 v96, v116, v96
	v_add_f32_e32 v96, v117, v96
	v_add_f32_e32 v96, v118, v96
	v_add_f32_e32 v96, v119, v96
	v_add_f32_e32 v96, v120, v96
	v_add_f32_e32 v96, v121, v96
	v_add_f32_e32 v96, v122, v96
	v_add_f32_e32 v96, v123, v96
	v_add_f32_e32 v96, v124, v96
	v_add_f32_e32 v96, v125, v96
	v_add_f32_e32 v96, v126, v96
	v_add_f32_e32 v96, v127, v96
	v_add_f32_e32 v96, v184, v96
	v_add_f32_e32 v112, v111, v96
	v_mov_b32_e32 v113, v112
	v_cvt_pk_bf16_f32 v96, v183, v188
	v_cvt_pk_bf16_f32 v97, v189, v190
	v_cvt_pk_bf16_f32 v98, v191, v192
	v_cvt_pk_bf16_f32 v99, v193, v194
	v_cvt_pk_bf16_f32 v100, v195, v196
	v_cvt_pk_bf16_f32 v101, v197, v198
	v_cvt_pk_bf16_f32 v102, v199, v200
	v_cvt_pk_bf16_f32 v103, v201, v202
	v_cvt_pk_bf16_f32 v104, v114, v115
	v_cvt_pk_bf16_f32 v105, v116, v117
	v_cvt_pk_bf16_f32 v106, v118, v119
	v_cvt_pk_bf16_f32 v107, v120, v121
	v_cvt_pk_bf16_f32 v108, v122, v123
	v_cvt_pk_bf16_f32 v109, v124, v125
	v_cvt_pk_bf16_f32 v110, v126, v127
	v_cvt_pk_bf16_f32 v111, v184, v111
	s_nop 1
	v_permlane32_swap_b32_e32 v112, v113
	v_permlane32_swap_b32_e32 v96, v98
	v_permlane32_swap_b32_e32 v97, v99
	v_permlane32_swap_b32_e32 v100, v102
	v_permlane32_swap_b32_e32 v101, v103
	v_permlane32_swap_b32_e32 v104, v106
	v_permlane32_swap_b32_e32 v105, v107
	v_permlane32_swap_b32_e32 v108, v110
	v_permlane32_swap_b32_e32 v109, v111
	s_cmp_lt_u32 s3, s58
	s_cselect_b64 s[22:23], -1, 0
	s_cmp_ge_u32 s3, s58
	s_cselect_b64 s[20:21], -1, 0
	s_and_b64 vcc, exec, s[20:21]
	s_cbranch_vccnz .LBB0_346
	v_add_co_u32_e32 v114, vcc, 0x593c000, v164
	s_nop 1
	v_addc_co_u32_e32 v115, vcc, 0, v165, vcc
	v_add_co_u32_e32 v116, vcc, 0x593c000, v168
	s_nop 1
	v_addc_co_u32_e32 v117, vcc, 0, v169, vcc
	global_load_dwordx4 v[146:149], v[114:115], off offset:1408
	global_load_dwordx4 v[150:153], v[116:117], off offset:2304
	v_add_co_u32_e32 v114, vcc, 0x593c000, v166
	s_nop 1
	v_addc_co_u32_e32 v115, vcc, 0, v167, vcc
	global_load_dwordx4 v[154:157], v[114:115], off offset:2304
